# hoist epilogue row-stat loads of in-proj and gate/up GEMM units to the unit start; epilogue starts with vmcnt(8) instead of a full drain
# baseline (speedup 1.0000x reference)
.LBB0_233:
	v_lshl_add_u32 v218, s4, 8, v234
	v_ashrrev_i32_e32 v219, 31, v218
	v_lshl_add_u64 v[218:219], v[218:219], 2, s[66:67]
	global_load_dword v244, v[218:219], off
	global_load_dword v245, v[218:219], off offset:64
	global_load_dword v246, v[218:219], off offset:128
	global_load_dword v247, v[218:219], off offset:192
	global_load_dword v248, v[218:219], off offset:512
	global_load_dword v249, v[218:219], off offset:576
	global_load_dword v250, v[218:219], off offset:640
	global_load_dword v251, v[218:219], off offset:704
	s_add_i32 s90, s90, 1
	s_mul_i32 s0, s90, s97
	s_mul_hi_u32 s1, s90, s96
	s_add_i32 s1, s1, s0
	s_mul_i32 s0, s90, s96
	s_add_u32 s0, s0, s2
	s_addc_u32 s1, s1, s3
	v_cmp_gt_i64_e32 vcc, s[0:1], v[180:181]
	v_cmp_lt_i64_e64 s[38:39], s[0:1], v[178:179]
	s_cbranch_vccnz .LBB0_235
	s_ashr_i32 s1, s0, 31
	s_lshr_b32 s1, s1, 29
	s_add_i32 s1, s0, s1
	s_ashr_i32 s5, s1, 3
	s_and_b32 s1, s1, -8
	s_sub_i32 s0, s0, s1
	s_cmp_lt_i32 s0, 0
	s_movk_i32 s1, 0xc9
	s_cselect_b32 s1, s1, 0xc8
	s_mul_i32 s0, s0, s1
	s_add_i32 s0, s0, s5
	s_mul_hi_i32 s1, s0, 0x1b4e81b5
	s_lshr_b32 s5, s1, 31
	s_ashr_i32 s1, s1, 4
	s_add_i32 s1, s1, s5
	s_mul_i32 s5, s1, 3
	s_sub_i32 s8, 32, s5
	s_min_i32 s8, s8, 3
	s_abs_i32 s10, s8
	v_cvt_f32_u32_e32 v0, s10
	s_sub_i32 s12, 0, s10
	s_mulk_i32 s1, 0x96
	s_sub_i32 s0, s0, s1
	v_rcp_iflag_f32_e32 v0, v0
	s_abs_i32 s1, s0
	s_xor_b32 s11, s0, s8
	s_ashr_i32 s11, s11, 31
	v_mul_f32_e32 v0, 0x4f7ffffe, v0
	v_cvt_u32_f32_e32 v0, v0
	s_nop 0
	v_readfirstlane_b32 s18, v0
	s_mul_i32 s12, s12, s18
	s_mul_hi_u32 s12, s18, s12
	s_add_i32 s18, s18, s12
	s_mul_hi_u32 s12, s1, s18
	s_mul_i32 s18, s12, s10
	s_sub_i32 s1, s1, s18
	s_add_i32 s34, s12, 1
	s_sub_i32 s18, s1, s10
	s_cmp_ge_u32 s1, s10
	s_cselect_b32 s12, s34, s12
	s_cselect_b32 s1, s18, s1
	s_add_i32 s18, s12, 1
	s_cmp_ge_u32 s1, s10
	s_cselect_b32 s1, s18, s12
	s_xor_b32 s1, s1, s11
	s_sub_i32 s72, s1, s11
	s_mul_i32 s1, s72, s8
	s_sub_i32 s0, s0, s1
	s_add_i32 s56, s5, s0

.LBB0_239:
	v_lshl_add_u32 v214, s4, 8, v234
	v_ashrrev_i32_e32 v215, 31, v214
	v_lshl_add_u64 v[130:131], v[214:215], 2, s[66:67]
	v_mov_b32_e32 v0, v244
	v_mov_b32_e32 v132, v245
	v_mov_b32_e32 v133, v246
	v_mov_b32_e32 v134, v247
	v_mov_b32_e32 v135, v248
	v_mov_b32_e32 v136, v249
	v_mov_b32_e32 v137, v250
	s_lshl_b32 s57, s44, 8
	v_mov_b32_e32 v130, v251
	s_add_i32 s6, s44, -8
	v_or_b32_e32 v210, 16, v214
	v_or_b32_e32 v206, 32, v214
	v_or_b32_e32 v202, 48, v214
	v_add_u32_e32 v198, 0x80, v214
	v_add_u32_e32 v194, 0x90, v214
	v_add_u32_e32 v190, 0xa0, v214
	v_add_u32_e32 v174, 0xb0, v214
	v_ashrrev_i32_e32 v211, 31, v210
	v_ashrrev_i32_e32 v207, 31, v206
	v_ashrrev_i32_e32 v203, 31, v202
	v_ashrrev_i32_e32 v199, 31, v198
	v_ashrrev_i32_e32 v195, 31, v194
	v_ashrrev_i32_e32 v191, 31, v190
	v_ashrrev_i32_e32 v175, 31, v174
	s_mov_b64 s[4:5], -1
	s_cmp_lt_u32 s6, 9
	s_waitcnt vmcnt(8) lgkmcnt(0)
	v_fmamk_f32 v0, v0, 0x3a000000, v224
	v_cmp_gt_f32_e32 vcc, s19, v0
	v_mul_f32_e32 v131, 0x4b800000, v0
	s_nop 0
	v_cndmask_b32_e32 v0, v0, v131, vcc
	v_rsq_f32_e32 v0, v0
	s_nop 0
	v_mul_f32_e32 v131, 0x45800000, v0
	v_cndmask_b32_e32 v216, v0, v131, vcc
	v_fmamk_f32 v0, v132, 0x3a000000, v224
	v_cmp_gt_f32_e32 vcc, s19, v0
	v_mul_f32_e32 v131, 0x4b800000, v0
	s_nop 0
	v_cndmask_b32_e32 v0, v0, v131, vcc
	v_rsq_f32_e32 v0, v0
	s_nop 0
	v_mul_f32_e32 v131, 0x45800000, v0
	v_cndmask_b32_e32 v212, v0, v131, vcc
	v_fmamk_f32 v0, v133, 0x3a000000, v224
	v_cmp_gt_f32_e32 vcc, s19, v0
	v_mul_f32_e32 v131, 0x4b800000, v0
	s_nop 0
	v_cndmask_b32_e32 v0, v0, v131, vcc
	v_rsq_f32_e32 v0, v0
	s_nop 0
	v_mul_f32_e32 v131, 0x45800000, v0
	v_cndmask_b32_e32 v208, v0, v131, vcc
	v_fmamk_f32 v0, v134, 0x3a000000, v224
	v_cmp_gt_f32_e32 vcc, s19, v0
	v_mul_f32_e32 v131, 0x4b800000, v0
	s_nop 0
	v_cndmask_b32_e32 v0, v0, v131, vcc
	v_rsq_f32_e32 v0, v0
	s_nop 0
	v_mul_f32_e32 v131, 0x45800000, v0
	v_cndmask_b32_e32 v204, v0, v131, vcc
	v_fmamk_f32 v0, v135, 0x3a000000, v224
	v_cmp_gt_f32_e32 vcc, s19, v0
	v_mul_f32_e32 v131, 0x4b800000, v0
	s_nop 0
	v_cndmask_b32_e32 v0, v0, v131, vcc
	v_rsq_f32_e32 v0, v0
	s_nop 0
	v_mul_f32_e32 v131, 0x45800000, v0
	v_cndmask_b32_e32 v200, v0, v131, vcc
	v_fmamk_f32 v0, v136, 0x3a000000, v224
	v_cmp_gt_f32_e32 vcc, s19, v0
	v_mul_f32_e32 v131, 0x4b800000, v0
	s_nop 0
	v_cndmask_b32_e32 v0, v0, v131, vcc
	v_rsq_f32_e32 v0, v0
	s_nop 0
	v_mul_f32_e32 v131, 0x45800000, v0
	v_cndmask_b32_e32 v196, v0, v131, vcc
	v_fmamk_f32 v0, v137, 0x3a000000, v224
	v_cmp_gt_f32_e32 vcc, s19, v0
	v_mul_f32_e32 v131, 0x4b800000, v0
	s_nop 0
	v_cndmask_b32_e32 v0, v0, v131, vcc
	v_rsq_f32_e32 v0, v0
	s_nop 0
	v_mul_f32_e32 v131, 0x45800000, v0
	v_cndmask_b32_e32 v192, v0, v131, vcc
	v_fmamk_f32 v0, v130, 0x3a000000, v224
	v_cmp_gt_f32_e32 vcc, s19, v0
	v_mul_f32_e32 v130, 0x4b800000, v0
	s_nop 0
	v_cndmask_b32_e32 v0, v0, v130, vcc
	v_rsq_f32_e32 v0, v0
	s_nop 0
	v_mul_f32_e32 v130, 0x45800000, v0
	v_cndmask_b32_e32 v176, v0, v130, vcc
	v_or_b32_e32 v0, s57, v236
	s_cbranch_scc1 .LBB0_306
	s_cmp_gt_i32 s44, 17
	s_cselect_b64 s[4:5], -1, 0
	v_lshlrev_b64 v[138:139], 14, v[214:215]
	v_pk_mul_f32 v[132:133], v[128:129], v[216:217] op_sel_hi:[1,0]
	v_pk_mul_f32 v[130:131], v[126:127], v[216:217] op_sel_hi:[1,0]
	v_pk_mul_f32 v[136:137], v[124:125], v[216:217] op_sel_hi:[1,0]
	v_pk_mul_f32 v[134:135], v[122:123], v[216:217] op_sel_hi:[1,0]
	s_mov_b64 s[6:7], -1
	s_and_b64 vcc, exec, s[4:5]
	v_lshl_add_u64 v[144:145], s[60:61], 0, v[138:139]
	s_cbranch_vccz .LBB0_242
	v_mul_f32_e32 v138, 0xbfb8aa3b, v130
	v_exp_f32_e32 v138, v138
	s_nop 0
	v_add_f32_e32 v138, 1.0, v138
	s_nop 0
	v_rcp_f32_e32 v138, v138
	s_nop 0
	v_mul_f32_e32 v139, 0xbfb8aa3b, v131
	v_exp_f32_e32 v139, v139
	s_nop 0
	v_add_f32_e32 v139, 1.0, v139
	s_nop 0
	v_rcp_f32_e32 v139, v139
	s_nop 0
	v_cvt_pk_bf16_f32 v138, v138, v139
	v_mul_f32_e32 v139, 0xbfb8aa3b, v132
	v_exp_f32_e32 v139, v139
	s_nop 0
	v_add_f32_e32 v139, 1.0, v139
	s_nop 0
	v_rcp_f32_e32 v139, v139
	s_nop 0
	v_mul_f32_e32 v140, 0xbfb8aa3b, v133
	v_exp_f32_e32 v140, v140
	s_nop 0
	v_add_f32_e32 v140, 1.0, v140
	s_nop 0
	v_rcp_f32_e32 v140, v140
	s_nop 0
	v_cvt_pk_bf16_f32 v139, v139, v140
	v_mul_f32_e32 v140, 0xbfb8aa3b, v134
	v_exp_f32_e32 v140, v140
	s_nop 0
	v_add_f32_e32 v140, 1.0, v140
	s_nop 0
	v_rcp_f32_e32 v140, v140
	s_nop 0
	v_mul_f32_e32 v141, 0xbfb8aa3b, v135
	v_exp_f32_e32 v141, v141
	s_nop 0
	v_add_f32_e32 v141, 1.0, v141
	s_nop 0
	v_rcp_f32_e32 v141, v141
	s_nop 0
	v_cvt_pk_bf16_f32 v140, v140, v141
	v_mul_f32_e32 v141, 0xbfb8aa3b, v136
	v_exp_f32_e32 v141, v141
	s_nop 0
	v_add_f32_e32 v141, 1.0, v141
	s_nop 0
	v_rcp_f32_e32 v141, v141
	s_nop 0
	v_mul_f32_e32 v142, 0xbfb8aa3b, v137
	v_exp_f32_e32 v142, v142
	s_nop 0
	v_add_f32_e32 v142, 1.0, v142
	s_mov_b64 s[6:7], 0
	v_rcp_f32_e32 v142, v142
	s_nop 0
	v_cvt_pk_bf16_f32 v141, v141, v142
	v_lshl_add_u64 v[142:143], v[0:1], 1, v[144:145]
	v_add_co_u32_e32 v142, vcc, 0xffffdc00, v142
	s_nop 1
	v_addc_co_u32_e32 v143, vcc, -1, v143, vcc
	flat_store_dwordx4 v[142:143], v[138:141] nt

.LBB0_1536:
	v_lshl_add_u32 v232, s11, 8, v146
	v_ashrrev_i32_e32 v233, 31, v232
	v_lshl_add_u64 v[232:233], v[232:233], 2, s[46:47]
	global_load_dword v244, v[232:233], off
	global_load_dword v245, v[232:233], off offset:64
	global_load_dword v246, v[232:233], off offset:128
	global_load_dword v247, v[232:233], off offset:192
	global_load_dword v248, v[232:233], off offset:512
	global_load_dword v249, v[232:233], off offset:576
	global_load_dword v250, v[232:233], off offset:640
	global_load_dword v251, v[232:233], off offset:704
	s_add_i32 s70, s70, 1
	s_mul_i32 s10, s70, s97
	s_mul_hi_u32 s12, s70, s96
	s_add_i32 s12, s12, s10
	s_mul_i32 s10, s70, s96
	s_add_u32 s38, s10, s2
	s_addc_u32 s39, s12, s3
	v_cmp_gt_i64_e32 vcc, s[38:39], v[188:189]
	v_cmp_lt_i64_e64 s[40:41], s[38:39], v[186:187]
	s_cbranch_vccnz .LBB0_1538
	s_ashr_i32 s10, s38, 31
	s_lshr_b32 s10, s10, 29
	s_add_i32 s10, s38, s10
	s_ashr_i32 s12, s10, 3
	s_and_b32 s10, s10, -8
	s_sub_i32 s10, s38, s10
	s_cmp_lt_i32 s10, 0
	s_movk_i32 s18, 0xb1
	s_cselect_b32 s18, s18, 0xb0
	s_mul_i32 s10, s10, s18
	s_add_i32 s10, s10, s12
	s_mul_hi_i32 s12, s10, 0x3e0f83e1
	s_lshr_b32 s18, s12, 31
	s_ashr_i32 s12, s12, 5
	s_add_i32 s12, s12, s18
	s_mul_i32 s18, s12, 3
	s_sub_i32 s34, 32, s18
	s_min_i32 s34, s34, 3
	s_abs_i32 s35, s34
	v_cvt_f32_u32_e32 v2, s35
	s_sub_i32 s39, 0, s35
	s_mulk_i32 s12, 0x84
	s_sub_i32 s10, s10, s12
	v_rcp_iflag_f32_e32 v2, v2
	s_abs_i32 s12, s10
	s_xor_b32 s38, s10, s34
	s_ashr_i32 s38, s38, 31
	v_mul_f32_e32 v2, 0x4f7ffffe, v2
	v_cvt_u32_f32_e32 v2, v2
	s_nop 0
	v_readfirstlane_b32 s50, v2
	s_mul_i32 s39, s39, s50
	s_mul_hi_u32 s39, s50, s39
	s_add_i32 s50, s50, s39
	s_mul_hi_u32 s39, s12, s50
	s_mul_i32 s50, s39, s35
	s_sub_i32 s12, s12, s50
	s_add_i32 s51, s39, 1
	s_sub_i32 s50, s12, s35
	s_cmp_ge_u32 s12, s35
	s_cselect_b32 s39, s51, s39
	s_cselect_b32 s12, s50, s12
	s_add_i32 s50, s39, 1
	s_cmp_ge_u32 s12, s35
	s_cselect_b32 s12, s50, s39
	s_xor_b32 s12, s12, s38
	s_sub_i32 s50, s12, s38
	s_mul_i32 s12, s50, s34
	s_sub_i32 s10, s10, s12
	s_add_i32 s52, s18, s10

.LBB0_1542:
	v_lshl_add_u32 v140, s11, 8, v146
	v_ashrrev_i32_e32 v141, 31, v140
	v_lshl_add_u64 v[142:143], v[140:141], 2, s[46:47]
	v_mov_b32_e32 v144, v244
	v_mov_b32_e32 v162, v245
	v_mov_b32_e32 v160, v246
	v_mov_b32_e32 v158, v247
	v_mov_b32_e32 v156, v248
	v_mov_b32_e32 v154, v249
	v_mov_b32_e32 v152, v250
	v_mov_b32_e32 v150, v251
	v_mov_b32_e32 v164, v122
	v_mov_b32_e32 v165, v126
	v_lshl_or_b32 v142, s8, 7, v148
	v_ashrrev_i32_e32 v143, 31, v142
	s_movk_i32 s6, 0x2c00
	v_or_b32_e32 v161, 16, v140
	v_or_b32_e32 v159, 32, v140
	v_or_b32_e32 v157, 48, v140
	v_add_u32_e32 v155, 0x80, v140
	v_add_u32_e32 v153, 0x90, v140
	v_add_u32_e32 v151, 0xa0, v140
	v_add_u32_e32 v141, 0xb0, v140
	s_waitcnt vmcnt(8) lgkmcnt(0)
	v_fmamk_f32 v144, v144, 0x3a000000, v224
	v_cmp_gt_f32_e32 vcc, s19, v144
	v_mul_f32_e32 v163, 0x4b800000, v144
	s_nop 0
	v_cndmask_b32_e32 v144, v144, v163, vcc
	v_rsq_f32_e32 v144, v144
	s_nop 0
	v_mul_f32_e32 v163, 0x45800000, v144
	v_cndmask_b32_e32 v144, v144, v163, vcc
	v_pk_mul_f32 v[164:165], v[164:165], v[144:145] op_sel_hi:[1,0]
	s_nop 0
	v_mul_f32_e32 v122, 0xbfb8aa3b, v165
	v_exp_f32_e32 v122, v122
	s_nop 0
	v_add_f32_e32 v122, 1.0, v122
	s_nop 0
	v_rcp_f32_e32 v122, v122
	s_nop 0
	v_mul_f32_e32 v122, v165, v122
	v_mov_b32_e32 v126, v123
	v_mul_f32_e32 v163, v164, v122
	v_pk_mul_f32 v[122:123], v[126:127], v[144:145] op_sel_hi:[1,0]
	s_nop 0
	v_mul_f32_e32 v126, 0xbfb8aa3b, v123
	v_exp_f32_e32 v126, v126
	s_nop 0
	v_add_f32_e32 v126, 1.0, v126
	s_nop 0
	v_rcp_f32_e32 v126, v126
	s_nop 0
	v_mul_f32_e32 v123, v123, v126
	v_mul_f32_e32 v126, v122, v123
	v_mov_b32_e32 v122, v124
	v_mov_b32_e32 v123, v128
	v_pk_mul_f32 v[122:123], v[122:123], v[144:145] op_sel_hi:[1,0]
	s_nop 0
	v_mul_f32_e32 v124, 0xbfb8aa3b, v123
	v_exp_f32_e32 v124, v124
	s_nop 0
	v_add_f32_e32 v124, 1.0, v124
	s_nop 0
	v_rcp_f32_e32 v124, v124
	s_nop 0
	v_mul_f32_e32 v123, v123, v124
	v_mov_b32_e32 v128, v125
	v_mul_f32_e32 v124, v122, v123
	v_pk_mul_f32 v[122:123], v[128:129], v[144:145] op_sel_hi:[1,0]
	s_nop 0
	v_mul_f32_e32 v125, 0xbfb8aa3b, v123
	v_exp_f32_e32 v125, v125
	s_nop 0
	v_add_f32_e32 v125, 1.0, v125
	s_nop 0
	v_rcp_f32_e32 v125, v125
	s_nop 0
	v_mul_f32_e32 v123, v123, v125
	v_mul_f32_e32 v125, v122, v123
	v_mov_b32_e32 v122, v114
	v_mov_b32_e32 v123, v118
	v_pk_mul_f32 v[122:123], v[122:123], v[144:145] op_sel_hi:[1,0]
	s_nop 0
	v_mul_f32_e32 v114, 0xbfb8aa3b, v123
	v_exp_f32_e32 v114, v114
	s_nop 0
	v_add_f32_e32 v114, 1.0, v114
	s_nop 0
	v_rcp_f32_e32 v114, v114
	s_nop 0
	v_mul_f32_e32 v114, v123, v114
	v_mov_b32_e32 v118, v115
	v_mul_f32_e32 v122, v122, v114
	v_pk_mul_f32 v[114:115], v[118:119], v[144:145] op_sel_hi:[1,0]
	s_nop 0
	v_mul_f32_e32 v118, 0xbfb8aa3b, v115
	v_exp_f32_e32 v118, v118
	s_nop 0
	v_add_f32_e32 v118, 1.0, v118
	s_nop 0
	v_rcp_f32_e32 v118, v118
	s_nop 0
	v_mul_f32_e32 v115, v115, v118
	v_mul_f32_e32 v123, v114, v115
	v_mov_b32_e32 v114, v116
	v_mov_b32_e32 v115, v120
	v_pk_mul_f32 v[114:115], v[114:115], v[144:145] op_sel_hi:[1,0]
	s_nop 0
	v_mul_f32_e32 v116, 0xbfb8aa3b, v115
	v_exp_f32_e32 v116, v116
	s_nop 0
	v_add_f32_e32 v116, 1.0, v116
	s_nop 0
	v_rcp_f32_e32 v116, v116
	s_nop 0
	v_mul_f32_e32 v115, v115, v116
	v_mov_b32_e32 v120, v117
	v_mul_f32_e32 v116, v114, v115
	v_pk_mul_f32 v[114:115], v[120:121], v[144:145] op_sel_hi:[1,0]
	s_nop 0
	v_mul_f32_e32 v117, 0xbfb8aa3b, v115
	v_exp_f32_e32 v117, v117
	s_nop 0
	v_add_f32_e32 v117, 1.0, v117
	s_nop 0
	v_rcp_f32_e32 v117, v117
	s_nop 0
	v_mul_f32_e32 v115, v115, v117
	v_mul_f32_e32 v114, v114, v115
	v_cvt_pk_bf16_f32 v118, v163, v126
	v_cvt_pk_bf16_f32 v119, v124, v125
	v_cvt_pk_bf16_f32 v120, v122, v123
	v_cvt_pk_bf16_f32 v121, v116, v114
	v_mov_b64_e32 v[114:115], s[44:45]
	v_mad_i64_i32 v[122:123], s[4:5], v140, s6, v[114:115]
	v_lshlrev_b64 v[116:117], 1, v[142:143]
	v_lshl_add_u64 v[122:123], v[122:123], 0, v[116:117]
	flat_store_dwordx4 v[122:123], v[118:121] nt
	s_nop 1
	v_fmamk_f32 v118, v162, 0x3a000000, v224
	v_cmp_gt_f32_e32 vcc, s19, v118
	v_mul_f32_e32 v119, 0x4b800000, v118
	v_mov_b32_e32 v120, v106
	v_cndmask_b32_e32 v118, v118, v119, vcc
	v_rsq_f32_e32 v118, v118
	v_mov_b32_e32 v121, v110
	v_mul_f32_e32 v119, 0x45800000, v118
	v_cndmask_b32_e32 v118, v118, v119, vcc
	v_pk_mul_f32 v[120:121], v[120:121], v[118:119] op_sel_hi:[1,0]
	s_nop 0
	v_mul_f32_e32 v106, 0xbfb8aa3b, v121
	v_exp_f32_e32 v106, v106
	s_nop 0
	v_add_f32_e32 v106, 1.0, v106
	s_nop 0
	v_rcp_f32_e32 v106, v106
	s_nop 0
	v_mul_f32_e32 v106, v121, v106
	v_mul_f32_e32 v119, v120, v106
	v_mov_b32_e32 v110, v107
	v_pk_mul_f32 v[106:107], v[110:111], v[118:119] op_sel_hi:[1,0]
	s_nop 0
	v_mul_f32_e32 v110, 0xbfb8aa3b, v107
	v_exp_f32_e32 v110, v110
	s_nop 0
	v_add_f32_e32 v110, 1.0, v110
	s_nop 0
	v_rcp_f32_e32 v110, v110
	s_nop 0
	v_mul_f32_e32 v107, v107, v110
	v_mul_f32_e32 v110, v106, v107
	v_mov_b32_e32 v106, v108
	v_mov_b32_e32 v107, v112
	v_pk_mul_f32 v[106:107], v[106:107], v[118:119] op_sel_hi:[1,0]
	s_nop 0
	v_mul_f32_e32 v108, 0xbfb8aa3b, v107
	v_exp_f32_e32 v108, v108
	s_nop 0
	v_add_f32_e32 v108, 1.0, v108
	s_nop 0
	v_rcp_f32_e32 v108, v108
	s_nop 0
	v_mul_f32_e32 v107, v107, v108
	v_mov_b32_e32 v112, v109
	v_mul_f32_e32 v108, v106, v107
	v_pk_mul_f32 v[106:107], v[112:113], v[118:119] op_sel_hi:[1,0]
	s_nop 0
	v_mul_f32_e32 v109, 0xbfb8aa3b, v107
	v_exp_f32_e32 v109, v109
	s_nop 0
	v_add_f32_e32 v109, 1.0, v109
	s_nop 0
	v_rcp_f32_e32 v109, v109
	s_nop 0
	v_mul_f32_e32 v107, v107, v109
	v_mul_f32_e32 v109, v106, v107
	v_mov_b32_e32 v106, v98
	v_mov_b32_e32 v107, v102
	v_pk_mul_f32 v[106:107], v[106:107], v[118:119] op_sel_hi:[1,0]
	s_nop 0
	v_mul_f32_e32 v98, 0xbfb8aa3b, v107
	v_exp_f32_e32 v98, v98
	s_nop 0
	v_add_f32_e32 v98, 1.0, v98
	s_nop 0
	v_rcp_f32_e32 v98, v98
	s_nop 0
	v_mul_f32_e32 v98, v107, v98
	v_mov_b32_e32 v102, v99
	v_mul_f32_e32 v106, v106, v98
	v_pk_mul_f32 v[98:99], v[102:103], v[118:119] op_sel_hi:[1,0]
	s_nop 0
	v_mul_f32_e32 v102, 0xbfb8aa3b, v99
	v_exp_f32_e32 v102, v102
	s_nop 0
	v_add_f32_e32 v102, 1.0, v102
	s_nop 0
	v_rcp_f32_e32 v102, v102
	s_nop 0
	v_mul_f32_e32 v99, v99, v102
	v_mul_f32_e32 v102, v98, v99
	v_mov_b32_e32 v98, v100
	v_mov_b32_e32 v99, v104
	v_pk_mul_f32 v[98:99], v[98:99], v[118:119] op_sel_hi:[1,0]
	s_nop 0
	v_mul_f32_e32 v100, 0xbfb8aa3b, v99
	v_exp_f32_e32 v100, v100
	s_nop 0
	v_add_f32_e32 v100, 1.0, v100
	s_nop 0
	v_rcp_f32_e32 v100, v100
	s_nop 0
	v_mul_f32_e32 v99, v99, v100
	v_mov_b32_e32 v104, v101
	v_mul_f32_e32 v103, v98, v99
	v_pk_mul_f32 v[98:99], v[104:105], v[118:119] op_sel_hi:[1,0]
	s_nop 0
	v_mul_f32_e32 v100, 0xbfb8aa3b, v99
	v_exp_f32_e32 v100, v100
	s_nop 0
	v_add_f32_e32 v100, 1.0, v100
	s_nop 0
	v_rcp_f32_e32 v100, v100
	s_nop 0
	v_mul_f32_e32 v99, v99, v100
	v_mul_f32_e32 v101, v98, v99
	v_cvt_pk_bf16_f32 v98, v119, v110
	v_cvt_pk_bf16_f32 v99, v108, v109
	v_cvt_pk_bf16_f32 v100, v106, v102
	v_cvt_pk_bf16_f32 v101, v103, v101
	v_mad_i64_i32 v[102:103], s[4:5], v161, s6, v[114:115]
	v_lshl_add_u64 v[102:103], v[102:103], 0, v[116:117]
	flat_store_dwordx4 v[102:103], v[98:101] nt
	s_nop 1
	v_fmamk_f32 v98, v160, 0x3a000000, v224
	v_cmp_gt_f32_e32 vcc, s19, v98
	v_mul_f32_e32 v99, 0x4b800000, v98
	v_mov_b32_e32 v100, v90
	v_cndmask_b32_e32 v98, v98, v99, vcc
	v_rsq_f32_e32 v98, v98
	v_mov_b32_e32 v101, v94
	v_mul_f32_e32 v99, 0x45800000, v98
	v_cndmask_b32_e32 v98, v98, v99, vcc
	v_pk_mul_f32 v[100:101], v[100:101], v[98:99] op_sel_hi:[1,0]
	s_nop 0
	v_mul_f32_e32 v90, 0xbfb8aa3b, v101
	v_exp_f32_e32 v90, v90
	s_nop 0
	v_add_f32_e32 v90, 1.0, v90
	s_nop 0
	v_rcp_f32_e32 v90, v90
	s_nop 0
	v_mul_f32_e32 v90, v101, v90
	v_mul_f32_e32 v99, v100, v90
	v_mov_b32_e32 v94, v91
	v_pk_mul_f32 v[90:91], v[94:95], v[98:99] op_sel_hi:[1,0]
	s_nop 0
	v_mul_f32_e32 v94, 0xbfb8aa3b, v91
	v_exp_f32_e32 v94, v94
	s_nop 0
	v_add_f32_e32 v94, 1.0, v94
	s_nop 0
	v_rcp_f32_e32 v94, v94
	s_nop 0
	v_mul_f32_e32 v91, v91, v94
	v_mul_f32_e32 v94, v90, v91
	v_mov_b32_e32 v90, v92
	v_mov_b32_e32 v91, v96
	v_pk_mul_f32 v[90:91], v[90:91], v[98:99] op_sel_hi:[1,0]
	s_nop 0
	v_mul_f32_e32 v92, 0xbfb8aa3b, v91
	v_exp_f32_e32 v92, v92
	s_nop 0
	v_add_f32_e32 v92, 1.0, v92
	s_nop 0
	v_rcp_f32_e32 v92, v92
	s_nop 0
	v_mul_f32_e32 v91, v91, v92
	v_mov_b32_e32 v96, v93
	v_mul_f32_e32 v92, v90, v91
	v_pk_mul_f32 v[90:91], v[96:97], v[98:99] op_sel_hi:[1,0]
	s_nop 0
	v_mul_f32_e32 v93, 0xbfb8aa3b, v91
	v_exp_f32_e32 v93, v93
	s_nop 0
	v_add_f32_e32 v93, 1.0, v93
	s_nop 0
	v_rcp_f32_e32 v93, v93
	s_nop 0
	v_mul_f32_e32 v91, v91, v93
	v_mul_f32_e32 v93, v90, v91
	v_mov_b32_e32 v90, v82
	v_mov_b32_e32 v91, v86
	v_pk_mul_f32 v[90:91], v[90:91], v[98:99] op_sel_hi:[1,0]
	s_nop 0
	v_mul_f32_e32 v82, 0xbfb8aa3b, v91
	v_exp_f32_e32 v82, v82
	s_nop 0
	v_add_f32_e32 v82, 1.0, v82
	s_nop 0
	v_rcp_f32_e32 v82, v82
	s_nop 0
	v_mul_f32_e32 v82, v91, v82
	v_mov_b32_e32 v86, v83
	v_mul_f32_e32 v90, v90, v82
	v_pk_mul_f32 v[82:83], v[86:87], v[98:99] op_sel_hi:[1,0]
	s_nop 0
	v_mul_f32_e32 v86, 0xbfb8aa3b, v83
	v_exp_f32_e32 v86, v86
	s_nop 0
	v_add_f32_e32 v86, 1.0, v86
	s_nop 0
	v_rcp_f32_e32 v86, v86
	s_nop 0
	v_mul_f32_e32 v83, v83, v86
	v_mul_f32_e32 v86, v82, v83
	v_mov_b32_e32 v82, v84
	v_mov_b32_e32 v83, v88
	v_pk_mul_f32 v[82:83], v[82:83], v[98:99] op_sel_hi:[1,0]
	s_nop 0
	v_mul_f32_e32 v84, 0xbfb8aa3b, v83
	v_exp_f32_e32 v84, v84
	s_nop 0
	v_add_f32_e32 v84, 1.0, v84
	s_nop 0
	v_rcp_f32_e32 v84, v84
	s_nop 0
	v_mul_f32_e32 v83, v83, v84
	v_mov_b32_e32 v88, v85
	v_mul_f32_e32 v87, v82, v83
	v_pk_mul_f32 v[82:83], v[88:89], v[98:99] op_sel_hi:[1,0]
	s_nop 0
	v_mul_f32_e32 v84, 0xbfb8aa3b, v83
	v_exp_f32_e32 v84, v84
	s_nop 0
	v_add_f32_e32 v84, 1.0, v84
	s_nop 0
	v_rcp_f32_e32 v84, v84
	s_nop 0
	v_mul_f32_e32 v83, v83, v84
	v_mul_f32_e32 v85, v82, v83
	v_cvt_pk_bf16_f32 v82, v99, v94
	v_cvt_pk_bf16_f32 v83, v92, v93
	v_cvt_pk_bf16_f32 v84, v90, v86
	v_cvt_pk_bf16_f32 v85, v87, v85
	v_mad_i64_i32 v[86:87], s[4:5], v159, s6, v[114:115]
	v_lshl_add_u64 v[86:87], v[86:87], 0, v[116:117]
	flat_store_dwordx4 v[86:87], v[82:85] nt
	s_nop 1
	v_fmamk_f32 v82, v158, 0x3a000000, v224
	v_cmp_gt_f32_e32 vcc, s19, v82
	v_mul_f32_e32 v83, 0x4b800000, v82
	v_mov_b32_e32 v84, v74
	v_cndmask_b32_e32 v82, v82, v83, vcc
	v_rsq_f32_e32 v82, v82
	v_mov_b32_e32 v85, v78
	v_mul_f32_e32 v83, 0x45800000, v82
	v_cndmask_b32_e32 v82, v82, v83, vcc
	v_pk_mul_f32 v[84:85], v[84:85], v[82:83] op_sel_hi:[1,0]
	s_nop 0
	v_mul_f32_e32 v74, 0xbfb8aa3b, v85
	v_exp_f32_e32 v74, v74
	s_nop 0
	v_add_f32_e32 v74, 1.0, v74
	s_nop 0
	v_rcp_f32_e32 v74, v74
	s_nop 0
	v_mul_f32_e32 v74, v85, v74
	v_mul_f32_e32 v83, v84, v74
	v_mov_b32_e32 v78, v75
	v_pk_mul_f32 v[74:75], v[78:79], v[82:83] op_sel_hi:[1,0]
	s_nop 0
	v_mul_f32_e32 v78, 0xbfb8aa3b, v75
	v_exp_f32_e32 v78, v78
	s_nop 0
	v_add_f32_e32 v78, 1.0, v78
	s_nop 0
	v_rcp_f32_e32 v78, v78
	s_nop 0
	v_mul_f32_e32 v75, v75, v78
	v_mul_f32_e32 v78, v74, v75
	v_mov_b32_e32 v74, v76
	v_mov_b32_e32 v75, v80
	v_pk_mul_f32 v[74:75], v[74:75], v[82:83] op_sel_hi:[1,0]
	s_nop 0
	v_mul_f32_e32 v76, 0xbfb8aa3b, v75
	v_exp_f32_e32 v76, v76
	s_nop 0
	v_add_f32_e32 v76, 1.0, v76
	s_nop 0
	v_rcp_f32_e32 v76, v76
	s_nop 0
	v_mul_f32_e32 v75, v75, v76
	v_mov_b32_e32 v80, v77
	v_mul_f32_e32 v76, v74, v75
	v_pk_mul_f32 v[74:75], v[80:81], v[82:83] op_sel_hi:[1,0]
	s_nop 0
	v_mul_f32_e32 v77, 0xbfb8aa3b, v75
	v_exp_f32_e32 v77, v77
	s_nop 0
	v_add_f32_e32 v77, 1.0, v77
	s_nop 0
	v_rcp_f32_e32 v77, v77
	s_nop 0
	v_mul_f32_e32 v75, v75, v77
	v_mul_f32_e32 v77, v74, v75
	v_mov_b32_e32 v74, v66
	v_mov_b32_e32 v75, v70
	v_pk_mul_f32 v[74:75], v[74:75], v[82:83] op_sel_hi:[1,0]
	s_nop 0
	v_mul_f32_e32 v66, 0xbfb8aa3b, v75
	v_exp_f32_e32 v66, v66
	s_nop 0
	v_add_f32_e32 v66, 1.0, v66
	s_nop 0
	v_rcp_f32_e32 v66, v66
	s_nop 0
	v_mul_f32_e32 v66, v75, v66
	v_mov_b32_e32 v70, v67
	v_mul_f32_e32 v74, v74, v66
	v_pk_mul_f32 v[66:67], v[70:71], v[82:83] op_sel_hi:[1,0]
	s_nop 0
	v_mul_f32_e32 v70, 0xbfb8aa3b, v67
	v_exp_f32_e32 v70, v70
	s_nop 0
	v_add_f32_e32 v70, 1.0, v70
	s_nop 0
	v_rcp_f32_e32 v70, v70
	s_nop 0
	v_mul_f32_e32 v67, v67, v70
	v_mul_f32_e32 v70, v66, v67
	v_mov_b32_e32 v66, v68
	v_mov_b32_e32 v67, v72
	v_pk_mul_f32 v[66:67], v[66:67], v[82:83] op_sel_hi:[1,0]
	s_nop 0
	v_mul_f32_e32 v68, 0xbfb8aa3b, v67
	v_exp_f32_e32 v68, v68
	s_nop 0
	v_add_f32_e32 v68, 1.0, v68
	s_nop 0
	v_rcp_f32_e32 v68, v68
	s_nop 0
	v_mul_f32_e32 v67, v67, v68
	v_mov_b32_e32 v72, v69
	v_mul_f32_e32 v71, v66, v67
	v_pk_mul_f32 v[66:67], v[72:73], v[82:83] op_sel_hi:[1,0]
	s_nop 0
	v_mul_f32_e32 v68, 0xbfb8aa3b, v67
	v_exp_f32_e32 v68, v68
	s_nop 0
	v_add_f32_e32 v68, 1.0, v68
	s_nop 0
	v_rcp_f32_e32 v68, v68
	s_nop 0
	v_mul_f32_e32 v67, v67, v68
	v_mul_f32_e32 v69, v66, v67
	v_cvt_pk_bf16_f32 v66, v83, v78
	v_cvt_pk_bf16_f32 v67, v76, v77
	v_cvt_pk_bf16_f32 v68, v74, v70
	v_cvt_pk_bf16_f32 v69, v71, v69
	v_mad_i64_i32 v[70:71], s[4:5], v157, s6, v[114:115]
	v_lshl_add_u64 v[70:71], v[70:71], 0, v[116:117]
	flat_store_dwordx4 v[70:71], v[66:69] nt
	s_nop 1
	v_fmamk_f32 v66, v156, 0x3a000000, v224
	v_cmp_gt_f32_e32 vcc, s19, v66
	v_mul_f32_e32 v67, 0x4b800000, v66
	v_mov_b32_e32 v68, v58
	v_cndmask_b32_e32 v66, v66, v67, vcc
	v_rsq_f32_e32 v66, v66
	v_mov_b32_e32 v69, v62
	v_mul_f32_e32 v67, 0x45800000, v66
	v_cndmask_b32_e32 v66, v66, v67, vcc
	v_pk_mul_f32 v[68:69], v[68:69], v[66:67] op_sel_hi:[1,0]
	s_nop 0
	v_mul_f32_e32 v58, 0xbfb8aa3b, v69
	v_exp_f32_e32 v58, v58
	s_nop 0
	v_add_f32_e32 v58, 1.0, v58
	s_nop 0
	v_rcp_f32_e32 v58, v58
	s_nop 0
	v_mul_f32_e32 v58, v69, v58
	v_mul_f32_e32 v67, v68, v58
	v_mov_b32_e32 v62, v59
	v_pk_mul_f32 v[58:59], v[62:63], v[66:67] op_sel_hi:[1,0]
	s_nop 0
	v_mul_f32_e32 v62, 0xbfb8aa3b, v59
	v_exp_f32_e32 v62, v62
	s_nop 0
	v_add_f32_e32 v62, 1.0, v62
	s_nop 0
	v_rcp_f32_e32 v62, v62
	s_nop 0
	v_mul_f32_e32 v59, v59, v62
	v_mul_f32_e32 v62, v58, v59
	v_mov_b32_e32 v58, v60
	v_mov_b32_e32 v59, v64
	v_pk_mul_f32 v[58:59], v[58:59], v[66:67] op_sel_hi:[1,0]
	s_nop 0
	v_mul_f32_e32 v60, 0xbfb8aa3b, v59
	v_exp_f32_e32 v60, v60
	s_nop 0
	v_add_f32_e32 v60, 1.0, v60
	s_nop 0
	v_rcp_f32_e32 v60, v60
	s_nop 0
	v_mul_f32_e32 v59, v59, v60
	v_mov_b32_e32 v64, v61
	v_mul_f32_e32 v60, v58, v59
	v_pk_mul_f32 v[58:59], v[64:65], v[66:67] op_sel_hi:[1,0]
	s_nop 0
	v_mul_f32_e32 v61, 0xbfb8aa3b, v59
	v_exp_f32_e32 v61, v61
	s_nop 0
	v_add_f32_e32 v61, 1.0, v61
	s_nop 0
	v_rcp_f32_e32 v61, v61
	s_nop 0
	v_mul_f32_e32 v59, v59, v61
	v_mul_f32_e32 v61, v58, v59
	v_mov_b32_e32 v58, v50
	v_mov_b32_e32 v59, v54
	v_pk_mul_f32 v[58:59], v[58:59], v[66:67] op_sel_hi:[1,0]
	s_nop 0
	v_mul_f32_e32 v50, 0xbfb8aa3b, v59
	v_exp_f32_e32 v50, v50
	s_nop 0
	v_add_f32_e32 v50, 1.0, v50
	s_nop 0
	v_rcp_f32_e32 v50, v50
	s_nop 0
	v_mul_f32_e32 v50, v59, v50
	v_mov_b32_e32 v54, v51
	v_mul_f32_e32 v58, v58, v50
	v_pk_mul_f32 v[50:51], v[54:55], v[66:67] op_sel_hi:[1,0]
	s_nop 0
	v_mul_f32_e32 v54, 0xbfb8aa3b, v51
	v_exp_f32_e32 v54, v54
	s_nop 0
	v_add_f32_e32 v54, 1.0, v54
	s_nop 0
	v_rcp_f32_e32 v54, v54
	s_nop 0
	v_mul_f32_e32 v51, v51, v54
	v_mul_f32_e32 v54, v50, v51
	v_mov_b32_e32 v50, v52
	v_mov_b32_e32 v51, v56
	v_pk_mul_f32 v[50:51], v[50:51], v[66:67] op_sel_hi:[1,0]
	s_nop 0
	v_mul_f32_e32 v52, 0xbfb8aa3b, v51
	v_exp_f32_e32 v52, v52
	s_nop 0
	v_add_f32_e32 v52, 1.0, v52
	s_nop 0
	v_rcp_f32_e32 v52, v52
	s_nop 0
	v_mul_f32_e32 v51, v51, v52
	v_mov_b32_e32 v56, v53
	v_mul_f32_e32 v55, v50, v51
	v_pk_mul_f32 v[50:51], v[56:57], v[66:67] op_sel_hi:[1,0]
	s_nop 0
	v_mul_f32_e32 v52, 0xbfb8aa3b, v51
	v_exp_f32_e32 v52, v52
	s_nop 0
	v_add_f32_e32 v52, 1.0, v52
	s_nop 0
	v_rcp_f32_e32 v52, v52
	s_nop 0
	v_mul_f32_e32 v51, v51, v52
	v_mul_f32_e32 v53, v50, v51
	v_cvt_pk_bf16_f32 v50, v67, v62
	v_cvt_pk_bf16_f32 v51, v60, v61
	v_cvt_pk_bf16_f32 v52, v58, v54
	v_cvt_pk_bf16_f32 v53, v55, v53
	v_mad_i64_i32 v[54:55], s[4:5], v155, s6, v[114:115]
	v_lshl_add_u64 v[54:55], v[54:55], 0, v[116:117]
	flat_store_dwordx4 v[54:55], v[50:53] nt
	s_nop 1
	v_fmamk_f32 v50, v154, 0x3a000000, v224
	v_cmp_gt_f32_e32 vcc, s19, v50
	v_mul_f32_e32 v51, 0x4b800000, v50
	v_mov_b32_e32 v52, v42
	v_cndmask_b32_e32 v50, v50, v51, vcc
	v_rsq_f32_e32 v50, v50
	v_mov_b32_e32 v53, v46
	v_mul_f32_e32 v51, 0x45800000, v50
	v_cndmask_b32_e32 v50, v50, v51, vcc
	v_pk_mul_f32 v[52:53], v[52:53], v[50:51] op_sel_hi:[1,0]
	s_nop 0
	v_mul_f32_e32 v42, 0xbfb8aa3b, v53
	v_exp_f32_e32 v42, v42
	s_nop 0
	v_add_f32_e32 v42, 1.0, v42
	s_nop 0
	v_rcp_f32_e32 v42, v42
	s_nop 0
	v_mul_f32_e32 v42, v53, v42
	v_mul_f32_e32 v51, v52, v42
	v_mov_b32_e32 v46, v43
	v_pk_mul_f32 v[42:43], v[46:47], v[50:51] op_sel_hi:[1,0]
	s_nop 0
	v_mul_f32_e32 v46, 0xbfb8aa3b, v43
	v_exp_f32_e32 v46, v46
	s_nop 0
	v_add_f32_e32 v46, 1.0, v46
	s_nop 0
	v_rcp_f32_e32 v46, v46
	s_nop 0
	v_mul_f32_e32 v43, v43, v46
	v_mul_f32_e32 v46, v42, v43
	v_mov_b32_e32 v42, v44
	v_mov_b32_e32 v43, v48
	v_pk_mul_f32 v[42:43], v[42:43], v[50:51] op_sel_hi:[1,0]
	s_nop 0
	v_mul_f32_e32 v44, 0xbfb8aa3b, v43
	v_exp_f32_e32 v44, v44
	s_nop 0
	v_add_f32_e32 v44, 1.0, v44
	s_nop 0
	v_rcp_f32_e32 v44, v44
	s_nop 0
	v_mul_f32_e32 v43, v43, v44
	v_mov_b32_e32 v48, v45
	v_mul_f32_e32 v44, v42, v43
	v_pk_mul_f32 v[42:43], v[48:49], v[50:51] op_sel_hi:[1,0]
	s_nop 0
	v_mul_f32_e32 v45, 0xbfb8aa3b, v43
	v_exp_f32_e32 v45, v45
	s_nop 0
	v_add_f32_e32 v45, 1.0, v45
	s_nop 0
	v_rcp_f32_e32 v45, v45
	s_nop 0
	v_mul_f32_e32 v43, v43, v45
	v_mul_f32_e32 v45, v42, v43
	v_mov_b32_e32 v42, v34
	v_mov_b32_e32 v43, v38
	v_pk_mul_f32 v[42:43], v[42:43], v[50:51] op_sel_hi:[1,0]
	s_nop 0
	v_mul_f32_e32 v34, 0xbfb8aa3b, v43
	v_exp_f32_e32 v34, v34
	s_nop 0
	v_add_f32_e32 v34, 1.0, v34
	s_nop 0
	v_rcp_f32_e32 v34, v34
	s_nop 0
	v_mul_f32_e32 v34, v43, v34
	v_mov_b32_e32 v38, v35
	v_mul_f32_e32 v42, v42, v34
	v_pk_mul_f32 v[34:35], v[38:39], v[50:51] op_sel_hi:[1,0]
	s_nop 0
	v_mul_f32_e32 v38, 0xbfb8aa3b, v35
	v_exp_f32_e32 v38, v38
	s_nop 0
	v_add_f32_e32 v38, 1.0, v38
	s_nop 0
	v_rcp_f32_e32 v38, v38
	s_nop 0
	v_mul_f32_e32 v35, v35, v38
	v_mul_f32_e32 v38, v34, v35
	v_mov_b32_e32 v34, v36
	v_mov_b32_e32 v35, v40
	v_pk_mul_f32 v[34:35], v[34:35], v[50:51] op_sel_hi:[1,0]
	s_nop 0
	v_mul_f32_e32 v36, 0xbfb8aa3b, v35
	v_exp_f32_e32 v36, v36
	s_nop 0
	v_add_f32_e32 v36, 1.0, v36
	s_nop 0
	v_rcp_f32_e32 v36, v36
	s_nop 0
	v_mul_f32_e32 v35, v35, v36
	v_mov_b32_e32 v40, v37
	v_mul_f32_e32 v39, v34, v35
	v_pk_mul_f32 v[34:35], v[40:41], v[50:51] op_sel_hi:[1,0]
	s_nop 0
	v_mul_f32_e32 v36, 0xbfb8aa3b, v35
	v_exp_f32_e32 v36, v36
	s_nop 0
	v_add_f32_e32 v36, 1.0, v36
	s_nop 0
	v_rcp_f32_e32 v36, v36
	s_nop 0
	v_mul_f32_e32 v35, v35, v36
	v_mul_f32_e32 v37, v34, v35
	v_cvt_pk_bf16_f32 v34, v51, v46
	v_cvt_pk_bf16_f32 v35, v44, v45
	v_cvt_pk_bf16_f32 v36, v42, v38
	v_cvt_pk_bf16_f32 v37, v39, v37
	v_mad_i64_i32 v[38:39], s[4:5], v153, s6, v[114:115]
	v_lshl_add_u64 v[38:39], v[38:39], 0, v[116:117]
	flat_store_dwordx4 v[38:39], v[34:37] nt
	s_nop 1
	v_fmamk_f32 v34, v152, 0x3a000000, v224
	v_cmp_gt_f32_e32 vcc, s19, v34
	v_mul_f32_e32 v35, 0x4b800000, v34
	v_mov_b32_e32 v36, v26
	v_cndmask_b32_e32 v34, v34, v35, vcc
	v_rsq_f32_e32 v34, v34
	v_mov_b32_e32 v37, v30
	v_mul_f32_e32 v35, 0x45800000, v34
	v_cndmask_b32_e32 v34, v34, v35, vcc
	v_pk_mul_f32 v[36:37], v[36:37], v[34:35] op_sel_hi:[1,0]
	s_nop 0
	v_mul_f32_e32 v26, 0xbfb8aa3b, v37
	v_exp_f32_e32 v26, v26
	s_nop 0
	v_add_f32_e32 v26, 1.0, v26
	s_nop 0
	v_rcp_f32_e32 v26, v26
	s_nop 0
	v_mul_f32_e32 v26, v37, v26
	v_mul_f32_e32 v35, v36, v26
	v_mov_b32_e32 v30, v27
	v_pk_mul_f32 v[26:27], v[30:31], v[34:35] op_sel_hi:[1,0]
	s_nop 0
	v_mul_f32_e32 v30, 0xbfb8aa3b, v27
	v_exp_f32_e32 v30, v30
	s_nop 0
	v_add_f32_e32 v30, 1.0, v30
	s_nop 0
	v_rcp_f32_e32 v30, v30
	s_nop 0
	v_mul_f32_e32 v27, v27, v30
	v_mul_f32_e32 v30, v26, v27
	v_mov_b32_e32 v26, v28
	v_mov_b32_e32 v27, v32
	v_pk_mul_f32 v[26:27], v[26:27], v[34:35] op_sel_hi:[1,0]
	s_nop 0
	v_mul_f32_e32 v28, 0xbfb8aa3b, v27
	v_exp_f32_e32 v28, v28
	s_nop 0
	v_add_f32_e32 v28, 1.0, v28
	s_nop 0
	v_rcp_f32_e32 v28, v28
	s_nop 0
	v_mul_f32_e32 v27, v27, v28
	v_mov_b32_e32 v32, v29
	v_mul_f32_e32 v28, v26, v27
	v_pk_mul_f32 v[26:27], v[32:33], v[34:35] op_sel_hi:[1,0]
	s_nop 0
	v_mul_f32_e32 v29, 0xbfb8aa3b, v27
	v_exp_f32_e32 v29, v29
	s_nop 0
	v_add_f32_e32 v29, 1.0, v29
	s_nop 0
	v_rcp_f32_e32 v29, v29
	s_nop 0
	v_mul_f32_e32 v27, v27, v29
	v_mul_f32_e32 v29, v26, v27
	v_mov_b32_e32 v26, v18
	v_mov_b32_e32 v27, v22
	v_pk_mul_f32 v[26:27], v[26:27], v[34:35] op_sel_hi:[1,0]
	s_nop 0
	v_mul_f32_e32 v18, 0xbfb8aa3b, v27
	v_exp_f32_e32 v18, v18
	s_nop 0
	v_add_f32_e32 v18, 1.0, v18
	s_nop 0
	v_rcp_f32_e32 v18, v18
	s_nop 0
	v_mul_f32_e32 v18, v27, v18
	v_mov_b32_e32 v22, v19
	v_mul_f32_e32 v26, v26, v18
	v_pk_mul_f32 v[18:19], v[22:23], v[34:35] op_sel_hi:[1,0]
	s_nop 0
	v_mul_f32_e32 v22, 0xbfb8aa3b, v19
	v_exp_f32_e32 v22, v22
	s_nop 0
	v_add_f32_e32 v22, 1.0, v22
	s_nop 0
	v_rcp_f32_e32 v22, v22
	s_nop 0
	v_mul_f32_e32 v19, v19, v22
	v_mul_f32_e32 v22, v18, v19
	v_mov_b32_e32 v18, v20
	v_mov_b32_e32 v19, v24
	v_pk_mul_f32 v[18:19], v[18:19], v[34:35] op_sel_hi:[1,0]
	s_nop 0
	v_mul_f32_e32 v20, 0xbfb8aa3b, v19
	v_exp_f32_e32 v20, v20
	s_nop 0
	v_add_f32_e32 v20, 1.0, v20
	s_nop 0
	v_rcp_f32_e32 v20, v20
	s_nop 0
	v_mul_f32_e32 v19, v19, v20
	v_mov_b32_e32 v24, v21
	v_mul_f32_e32 v23, v18, v19
	v_pk_mul_f32 v[18:19], v[24:25], v[34:35] op_sel_hi:[1,0]
	s_nop 0
	v_mul_f32_e32 v20, 0xbfb8aa3b, v19
	v_exp_f32_e32 v20, v20
	s_nop 0
	v_add_f32_e32 v20, 1.0, v20
	s_nop 0
	v_rcp_f32_e32 v20, v20
	s_nop 0
	v_mul_f32_e32 v19, v19, v20
	v_mul_f32_e32 v21, v18, v19
	v_cvt_pk_bf16_f32 v18, v35, v30
	v_cvt_pk_bf16_f32 v19, v28, v29
	v_cvt_pk_bf16_f32 v20, v26, v22
	v_cvt_pk_bf16_f32 v21, v23, v21
	v_mad_i64_i32 v[22:23], s[4:5], v151, s6, v[114:115]
	v_lshl_add_u64 v[22:23], v[22:23], 0, v[116:117]
	flat_store_dwordx4 v[22:23], v[18:21] nt
	s_nop 1
	v_fmamk_f32 v18, v150, 0x3a000000, v224
	v_cmp_gt_f32_e32 vcc, s19, v18
	v_mul_f32_e32 v19, 0x4b800000, v18
	v_mov_b32_e32 v20, v10
	v_cndmask_b32_e32 v18, v18, v19, vcc
	v_rsq_f32_e32 v18, v18
	v_mov_b32_e32 v21, v14
	v_mul_f32_e32 v19, 0x45800000, v18
	v_cndmask_b32_e32 v18, v18, v19, vcc
	v_pk_mul_f32 v[20:21], v[20:21], v[18:19] op_sel_hi:[1,0]
	s_nop 0
	v_mul_f32_e32 v10, 0xbfb8aa3b, v21
	v_exp_f32_e32 v10, v10
	s_nop 0
	v_add_f32_e32 v10, 1.0, v10
	s_nop 0
	v_rcp_f32_e32 v10, v10
	s_nop 0
	v_mul_f32_e32 v10, v21, v10
	v_mul_f32_e32 v19, v20, v10
	v_mov_b32_e32 v14, v11
	v_pk_mul_f32 v[10:11], v[14:15], v[18:19] op_sel_hi:[1,0]
	s_nop 0
	v_mul_f32_e32 v14, 0xbfb8aa3b, v11
	v_exp_f32_e32 v14, v14
	s_nop 0
	v_add_f32_e32 v14, 1.0, v14
	s_nop 0
	v_rcp_f32_e32 v14, v14
	s_nop 0
	v_mul_f32_e32 v11, v11, v14
	v_mul_f32_e32 v14, v10, v11
	v_mov_b32_e32 v10, v12
	v_mov_b32_e32 v11, v16
	v_pk_mul_f32 v[10:11], v[10:11], v[18:19] op_sel_hi:[1,0]
	s_nop 0
	v_mul_f32_e32 v12, 0xbfb8aa3b, v11
	v_exp_f32_e32 v12, v12
	s_nop 0
	v_add_f32_e32 v12, 1.0, v12
	s_nop 0
	v_rcp_f32_e32 v12, v12
	s_nop 0
	v_mul_f32_e32 v11, v11, v12
	v_mov_b32_e32 v16, v13
	v_mul_f32_e32 v12, v10, v11
	v_pk_mul_f32 v[10:11], v[16:17], v[18:19] op_sel_hi:[1,0]
	s_nop 0
	v_mul_f32_e32 v13, 0xbfb8aa3b, v11
	v_exp_f32_e32 v13, v13
	s_nop 0
	v_add_f32_e32 v13, 1.0, v13
	s_nop 0
	v_rcp_f32_e32 v13, v13
	s_nop 0
	v_mul_f32_e32 v11, v11, v13
	v_mul_f32_e32 v13, v10, v11
	v_mov_b32_e32 v10, v2
	v_mov_b32_e32 v11, v6
	v_pk_mul_f32 v[10:11], v[10:11], v[18:19] op_sel_hi:[1,0]
	s_nop 0
	v_mul_f32_e32 v2, 0xbfb8aa3b, v11
	v_exp_f32_e32 v2, v2
	s_nop 0
	v_add_f32_e32 v2, 1.0, v2
	s_nop 0
	v_rcp_f32_e32 v2, v2
	s_nop 0
	v_mul_f32_e32 v2, v11, v2
	v_mov_b32_e32 v6, v3
	v_mul_f32_e32 v10, v10, v2
	v_pk_mul_f32 v[2:3], v[6:7], v[18:19] op_sel_hi:[1,0]
	s_nop 0
	v_mul_f32_e32 v6, 0xbfb8aa3b, v3
	v_exp_f32_e32 v6, v6
	s_nop 0
	v_add_f32_e32 v6, 1.0, v6
	s_nop 0
	v_rcp_f32_e32 v6, v6
	s_nop 0
	v_mul_f32_e32 v3, v3, v6
	v_mul_f32_e32 v6, v2, v3
	v_mov_b32_e32 v2, v4
	v_mov_b32_e32 v3, v8
	v_pk_mul_f32 v[2:3], v[2:3], v[18:19] op_sel_hi:[1,0]
	s_nop 0
	v_mul_f32_e32 v4, 0xbfb8aa3b, v3
	v_exp_f32_e32 v4, v4
	s_nop 0
	v_add_f32_e32 v4, 1.0, v4
	s_nop 0
	v_rcp_f32_e32 v4, v4
	s_nop 0
	v_mul_f32_e32 v3, v3, v4
	v_mov_b32_e32 v8, v5
	v_mul_f32_e32 v7, v2, v3
	v_pk_mul_f32 v[2:3], v[8:9], v[18:19] op_sel_hi:[1,0]
	s_nop 0
	v_mul_f32_e32 v4, 0xbfb8aa3b, v3
	v_exp_f32_e32 v4, v4
	s_nop 0
	v_add_f32_e32 v4, 1.0, v4
	s_nop 0
	v_rcp_f32_e32 v4, v4
	s_nop 0
	v_mul_f32_e32 v3, v3, v4
	v_mul_f32_e32 v5, v2, v3
	v_cvt_pk_bf16_f32 v2, v19, v14
	v_cvt_pk_bf16_f32 v3, v12, v13
	v_cvt_pk_bf16_f32 v4, v10, v6
	v_cvt_pk_bf16_f32 v5, v7, v5
	v_mad_i64_i32 v[6:7], s[4:5], v141, s6, v[114:115]
	v_lshl_add_u64 v[6:7], v[6:7], 0, v[116:117]
	s_mov_b64 s[4:5], -1
	s_andn2_b64 vcc, exec, s[40:41]
	flat_store_dwordx4 v[6:7], v[2:5] nt
	s_cbranch_vccnz .LBB0_1535
	s_andn2_b64 vcc, exec, s[42:43]
	s_cbranch_vccnz .LBB0_1534
	s_barrier
	s_branch .LBB0_1534
